# w_uq GEMM epilogue: rotary cos/sin fetched up front into dead fragment registers (two batches per unit) instead of load + vmcnt(0) behind the previous stores for every rotary column block
# speedup vs baseline: 1.0105x; 1.0105x over previous
; #define PG8_STAGE(bufoff, gbase, voff) do { _Pragma("unroll") for (int _i = 0; _i < 2; ++_i) \
;         __builtin_amdgcn_global_load_lds((const unsigned*)((const char*)(gbase) + (voff)[_i]), (PG8_LAS unsigned*)(lds + (bufoff) + ldsw + _i * 8192), 16, 0, 0); } while (0)
; #define PG8_LDA(dst, b, h) do { _Pragma("unroll") for (int m = 0; m < 4; ++m) _Pragma("unroll") for (int k = 0; k < 2; ++k) dst[m][k] = *(const PG8_LAS bf16x8*)(lds + PG8_SA(b, h) + aoff + m * 2048 + k * 1024); } while (0)
; #define PG8_WAIT_V(n) asm volatile("s_waitcnt vmcnt(" #n ")" ::: "memory")
; template <bool FP8, class Epi, class Sched>
; __device__ __forceinline__ void gemm_phase(PG8_LAS unsigned char* lds, const Gemm g, const Sched& S, const Epi& E) {
;     ...
;         for (int t = 0; t < nt; t += 2) {
;             const bool last = (t == nt - 2);
;             const char* a1 = cA + (size_t)(t + 1) * kstep;
;             const char* a2 = last ? nA : cA + (size_t)(t + 2) * kstep; const char* b2 = last ? nB : cB + (size_t)(t + 2) * kstep;
;             const char* a3 = a2 + kstep; const char* b3 = b2 + kstep;
;             if (last && has_next) S.a_ready(nxt);
;             PG8_LDB(B0, 0, 0); PG8_SCHED; PG8_LDA(At, 0, 0); PG8_STAGE(PG8_SA(1, 1), a1 + hstepA, voffA);
;             PG8_WAIT_L(8); PG8_BAR; PG8_WAIT_L(0); PG8_MMA(0, 0, At, B0); PG8_BAR; PG8_SCHED;
;             PG8_LDB(B1, 0, 1); PG8_STAGE(PG8_SB(0, 0), b2, voffB);
;             PG8_BAR; PG8_WAIT_L(0); PG8_MMA(0, 1, At, B1); PG8_BAR;
;             PG8_LDA(At, 0, 1); PG8_STAGE(PG8_SA(0, 0), a2, voffA);
;             PG8_BAR; PG8_WAIT_L(0); PG8_MMA(1, 0, At, B0); PG8_BAR; PG8_SCHED;
;             PG8_STAGE(PG8_SB(0, 1), b2 + hstep, voffB);
;             PG8_WAIT_V(6); PG8_BAR; PG8_MMA(1, 1, At, B1); PG8_BAR;
;             PG8_LDB(B0, 1, 0); PG8_SCHED; PG8_LDA(At, 1, 0); PG8_STAGE(PG8_SA(0, 1), a2 + hstepA, voffA);
;             PG8_WAIT_L(8); PG8_BAR; PG8_WAIT_L(0); PG8_MMA(0, 0, At, B0); PG8_BAR; PG8_SCHED;
;             PG8_LDB(B1, 1, 1); PG8_STAGE(PG8_SB(1, 0), b3, voffB);
;             PG8_BAR; PG8_WAIT_L(0); PG8_MMA(0, 1, At, B1); PG8_BAR;
;             PG8_LDA(At, 1, 1); PG8_STAGE(PG8_SA(1, 0), a3, voffA);
;             PG8_BAR; PG8_WAIT_L(0); PG8_MMA(1, 0, At, B0); PG8_BAR; PG8_SCHED;
;             PG8_STAGE(PG8_SB(1, 1), b3 + hstep, voffB);
;             PG8_WAIT_V(6); PG8_BAR; PG8_MMA(1, 1, At, B1); PG8_BAR;
.LBB0_1090:
	s_add_u32 s10, s16, 0x100
	s_addc_u32 s11, s17, 0
	s_add_i32 s30, 0, 0x10000
	v_add_u32_e32 v0, s30, v183
	ds_read_b128 v[10:13], v0
	ds_read_b128 v[14:17], v0 offset:1024
	ds_read_b128 v[2:5], v0 offset:2048
	ds_read_b128 v[6:9], v0 offset:3072
	s_cmp_eq_u32 s73, 8
	s_cselect_b32 s19, s1, s11
	s_cselect_b32 s18, s0, s10
	s_cselect_b32 s13, s15, s72
	s_cselect_b32 s12, s14, s71
	v_lshl_add_u64 v[18:19], s[16:17], 0, v[162:163]
	s_add_i32 m0, s24, 0xc000
	ds_read_b128 v[186:189], v184
	ds_read_b128 v[190:193], v184 offset:1024
	ds_read_b128 v[194:197], v184 offset:2048
	ds_read_b128 v[198:201], v184 offset:3072
	ds_read_b128 v[202:205], v184 offset:4096
	ds_read_b128 v[206:209], v184 offset:5120
	ds_read_b128 v[236:239], v184 offset:6144
	ds_read_b128 v[240:243], v184 offset:7168
	global_load_lds_dwordx4 v[18:19], off
	v_lshl_add_u64 v[18:19], s[16:17], 0, v[164:165]
	s_add_i32 m0, s24, 0xe000
	s_nop 0
	global_load_lds_dwordx4 v[18:19], off
	s_waitcnt lgkmcnt(8)
	s_barrier
	s_waitcnt lgkmcnt(0)
	s_setprio 1
	s_waitcnt lgkmcnt(0)
	s_nop 1
	v_mfma_scale_f32_16x16x128_f8f6f4 v[150:153], v[10:17], v[186:193], v[150:153], v174, v174 op_sel_hi:[0,0,0]
	s_nop 1
	v_mfma_scale_f32_16x16x128_f8f6f4 v[146:149], v[2:9], v[186:193], v[146:149], v174, v174 op_sel_hi:[0,0,0]
	s_nop 1
	v_mfma_scale_f32_16x16x128_f8f6f4 v[134:137], v[10:17], v[194:201], v[134:137], v174, v174 op_sel_hi:[0,0,0]
	s_nop 1
	v_mfma_scale_f32_16x16x128_f8f6f4 v[130:133], v[2:9], v[194:201], v[130:133], v174, v174 op_sel_hi:[0,0,0]
	s_nop 1
	v_mfma_scale_f32_16x16x128_f8f6f4 v[118:121], v[10:17], v[202:209], v[118:121], v174, v174 op_sel_hi:[0,0,0]
	s_nop 1
	v_mfma_scale_f32_16x16x128_f8f6f4 v[114:117], v[2:9], v[202:209], v[114:117], v174, v174 op_sel_hi:[0,0,0]
	s_nop 1
	v_mfma_scale_f32_16x16x128_f8f6f4 v[102:105], v[10:17], v[236:243], v[102:105], v174, v174 op_sel_hi:[0,0,0]
	s_nop 1
	v_mfma_scale_f32_16x16x128_f8f6f4 v[98:101], v[2:9], v[236:243], v[98:101], v174, v174 op_sel_hi:[0,0,0]
	s_setprio 0
	s_barrier
	s_add_i32 s31, 0, 0x14000
	s_add_i32 s16, s30, s23
	v_add_u32_e32 v0, s31, v183
	v_lshl_add_u64 v[166:167], s[12:13], 0, v[158:159]
	s_mov_b32 m0, s16
	ds_read_b128 v[210:213], v0
	ds_read_b128 v[214:217], v0 offset:1024
	ds_read_b128 v[18:21], v0 offset:2048
	ds_read_b128 v[22:25], v0 offset:3072
	global_load_lds_dwordx4 v[166:167], off
	v_lshl_add_u64 v[168:169], s[12:13], 0, v[154:155]
	s_add_i32 m0, s16, 0x2000
	s_nop 0
	global_load_lds_dwordx4 v[168:169], off
	s_barrier
	s_waitcnt lgkmcnt(0)
	s_setprio 1
	s_waitcnt lgkmcnt(0)
	s_nop 1
	v_mfma_scale_f32_16x16x128_f8f6f4 v[142:145], v[210:217], v[186:193], v[142:145], v174, v174 op_sel_hi:[0,0,0]
	s_nop 1
	v_mfma_scale_f32_16x16x128_f8f6f4 v[138:141], v[18:25], v[186:193], v[138:141], v174, v174 op_sel_hi:[0,0,0]
	s_nop 1
	v_mfma_scale_f32_16x16x128_f8f6f4 v[126:129], v[210:217], v[194:201], v[126:129], v174, v174 op_sel_hi:[0,0,0]
	s_nop 1
	v_mfma_scale_f32_16x16x128_f8f6f4 v[122:125], v[18:25], v[194:201], v[122:125], v174, v174 op_sel_hi:[0,0,0]
	s_nop 1
	v_mfma_scale_f32_16x16x128_f8f6f4 v[110:113], v[210:217], v[202:209], v[110:113], v174, v174 op_sel_hi:[0,0,0]
	s_nop 1
	v_mfma_scale_f32_16x16x128_f8f6f4 v[106:109], v[18:25], v[202:209], v[106:109], v174, v174 op_sel_hi:[0,0,0]
	s_nop 1
	v_mfma_scale_f32_16x16x128_f8f6f4 v[94:97], v[210:217], v[236:243], v[94:97], v174, v174 op_sel_hi:[0,0,0]
	s_nop 1
	v_mfma_scale_f32_16x16x128_f8f6f4 v[90:93], v[18:25], v[236:243], v[90:93], v174, v174 op_sel_hi:[0,0,0]
	s_setprio 0
	s_mov_b32 m0, s24
	v_lshl_add_u64 v[170:171], s[18:19], 0, v[160:161]
	s_barrier
	ds_read_b128 v[186:189], v184 offset:16384
	ds_read_b128 v[190:193], v184 offset:17408
	ds_read_b128 v[194:197], v184 offset:18432
	ds_read_b128 v[198:201], v184 offset:19456
	ds_read_b128 v[202:205], v184 offset:20480
	ds_read_b128 v[206:209], v184 offset:21504
	ds_read_b128 v[236:239], v184 offset:22528
	ds_read_b128 v[240:243], v184 offset:23552
	global_load_lds_dwordx4 v[170:171], off
	v_lshl_add_u64 v[172:173], s[18:19], 0, v[156:157]
	s_mov_b32 m0, s25
	s_nop 0
	global_load_lds_dwordx4 v[172:173], off
	s_barrier
	s_waitcnt lgkmcnt(0)
	s_setprio 1
	s_waitcnt lgkmcnt(0)
	s_nop 1
	v_mfma_scale_f32_16x16x128_f8f6f4 v[86:89], v[10:17], v[186:193], v[86:89], v174, v174 op_sel_hi:[0,0,0]
	s_nop 1
	v_mfma_scale_f32_16x16x128_f8f6f4 v[82:85], v[2:9], v[186:193], v[82:85], v174, v174 op_sel_hi:[0,0,0]
	s_nop 1
	v_mfma_scale_f32_16x16x128_f8f6f4 v[70:73], v[10:17], v[194:201], v[70:73], v174, v174 op_sel_hi:[0,0,0]
	s_nop 1
	v_mfma_scale_f32_16x16x128_f8f6f4 v[66:69], v[2:9], v[194:201], v[66:69], v174, v174 op_sel_hi:[0,0,0]
	s_nop 1
	v_mfma_scale_f32_16x16x128_f8f6f4 v[54:57], v[10:17], v[202:209], v[54:57], v174, v174 op_sel_hi:[0,0,0]
	s_nop 1
	v_mfma_scale_f32_16x16x128_f8f6f4 v[50:53], v[2:9], v[202:209], v[50:53], v174, v174 op_sel_hi:[0,0,0]
	s_nop 1
	v_mfma_scale_f32_16x16x128_f8f6f4 v[38:41], v[10:17], v[236:243], v[38:41], v174, v174 op_sel_hi:[0,0,0]
	s_nop 1
	v_mfma_scale_f32_16x16x128_f8f6f4 v[34:37], v[2:9], v[236:243], v[34:37], v174, v174 op_sel_hi:[0,0,0]
	s_setprio 0
	s_barrier
	s_add_u32 s16, s12, 0x30000
	s_addc_u32 s17, s13, 0
	s_add_i32 s30, s31, s23
	v_lshl_add_u64 v[2:3], s[16:17], 0, v[158:159]
	s_mov_b32 m0, s30
	s_nop 0
	global_load_lds_dwordx4 v[2:3], off
	v_lshl_add_u64 v[2:3], s[16:17], 0, v[154:155]
	s_add_i32 m0, s30, 0x2000
	s_nop 0
	global_load_lds_dwordx4 v[2:3], off
	s_waitcnt vmcnt(6)
	s_barrier
; #define PG8_STAGE(bufoff, gbase, voff) do { _Pragma("unroll") for (int _i = 0; _i < 2; ++_i) \
;         __builtin_amdgcn_global_load_lds((const unsigned*)((const char*)(gbase) + (voff)[_i]), (PG8_LAS unsigned*)(lds + (bufoff) + ldsw + _i * 8192), 16, 0, 0); } while (0)
; #define PG8_LDA(dst, b, h) do { _Pragma("unroll") for (int m = 0; m < 4; ++m) _Pragma("unroll") for (int k = 0; k < 2; ++k) dst[m][k] = *(const PG8_LAS bf16x8*)(lds + PG8_SA(b, h) + aoff + m * 2048 + k * 1024); } while (0)
; #define PG8_WAIT_V(n) asm volatile("s_waitcnt vmcnt(" #n ")" ::: "memory")
; template <bool FP8, class Epi, class Sched>
; __device__ __forceinline__ void gemm_phase(PG8_LAS unsigned char* lds, const Gemm g, const Sched& S, const Epi& E) {
;     ...
;         for (int t = 0; t < nt; t += 2) {
;             const bool last = (t == nt - 2);
;             const char* a1 = cA + (size_t)(t + 1) * kstep;
;             const char* a2 = last ? nA : cA + (size_t)(t + 2) * kstep; const char* b2 = last ? nB : cB + (size_t)(t + 2) * kstep;
;             const char* a3 = a2 + kstep; const char* b3 = b2 + kstep;
;             if (last && has_next) S.a_ready(nxt);
;             PG8_LDB(B0, 0, 0); PG8_SCHED; PG8_LDA(At, 0, 0); PG8_STAGE(PG8_SA(1, 1), a1 + hstepA, voffA);
;             PG8_WAIT_L(8); PG8_BAR; PG8_WAIT_L(0); PG8_MMA(0, 0, At, B0); PG8_BAR; PG8_SCHED;
;             PG8_LDB(B1, 0, 1); PG8_STAGE(PG8_SB(0, 0), b2, voffB);
;             PG8_BAR; PG8_WAIT_L(0); PG8_MMA(0, 1, At, B1); PG8_BAR;
;             PG8_LDA(At, 0, 1); PG8_STAGE(PG8_SA(0, 0), a2, voffA);
;             PG8_BAR; PG8_WAIT_L(0); PG8_MMA(1, 0, At, B0); PG8_BAR; PG8_SCHED;
;             PG8_STAGE(PG8_SB(0, 1), b2 + hstep, voffB);
;             PG8_WAIT_V(6); PG8_BAR; PG8_MMA(1, 1, At, B1); PG8_BAR;
;             PG8_LDB(B0, 1, 0); PG8_SCHED; PG8_LDA(At, 1, 0); PG8_STAGE(PG8_SA(0, 1), a2 + hstepA, voffA);
;             PG8_WAIT_L(8); PG8_BAR; PG8_WAIT_L(0); PG8_MMA(0, 0, At, B0); PG8_BAR; PG8_SCHED;
;             PG8_LDB(B1, 1, 1); PG8_STAGE(PG8_SB(1, 0), b3, voffB);
;             PG8_BAR; PG8_WAIT_L(0); PG8_MMA(0, 1, At, B1); PG8_BAR;
;             PG8_LDA(At, 1, 1); PG8_STAGE(PG8_SA(1, 0), a3, voffA);
;             PG8_BAR; PG8_WAIT_L(0); PG8_MMA(1, 0, At, B0); PG8_BAR; PG8_SCHED;
;             PG8_STAGE(PG8_SB(1, 1), b3 + hstep, voffB);
;             PG8_WAIT_V(6); PG8_BAR; PG8_MMA(1, 1, At, B1); PG8_BAR;
	s_setprio 1
	s_nop 1
	v_mfma_scale_f32_16x16x128_f8f6f4 v[78:81], v[210:217], v[186:193], v[78:81], v174, v174 op_sel_hi:[0,0,0]
	s_nop 1
	v_mfma_scale_f32_16x16x128_f8f6f4 v[74:77], v[18:25], v[186:193], v[74:77], v174, v174 op_sel_hi:[0,0,0]
	s_nop 1
	v_mfma_scale_f32_16x16x128_f8f6f4 v[62:65], v[210:217], v[194:201], v[62:65], v174, v174 op_sel_hi:[0,0,0]
	s_nop 1
	v_mfma_scale_f32_16x16x128_f8f6f4 v[58:61], v[18:25], v[194:201], v[58:61], v174, v174 op_sel_hi:[0,0,0]
	s_nop 1
	v_mfma_scale_f32_16x16x128_f8f6f4 v[46:49], v[210:217], v[202:209], v[46:49], v174, v174 op_sel_hi:[0,0,0]
	s_nop 1
	v_mfma_scale_f32_16x16x128_f8f6f4 v[42:45], v[18:25], v[202:209], v[42:45], v174, v174 op_sel_hi:[0,0,0]
	s_nop 1
	v_mfma_scale_f32_16x16x128_f8f6f4 v[30:33], v[210:217], v[236:243], v[30:33], v174, v174 op_sel_hi:[0,0,0]
	s_nop 1
	v_mfma_scale_f32_16x16x128_f8f6f4 v[26:29], v[18:25], v[236:243], v[26:29], v174, v174 op_sel_hi:[0,0,0]
	s_setprio 0
	s_add_i32 s30, 0, 0x18000
	v_add_u32_e32 v0, s30, v183
	s_barrier
	ds_read_b128 v[2:5], v0
	ds_read_b128 v[6:9], v0 offset:1024
	ds_read_b128 v[10:13], v0 offset:2048
	ds_read_b128 v[14:17], v0 offset:3072
	s_add_u32 s16, s18, 0x30000
	s_addc_u32 s17, s19, 0
	s_mov_b32 m0, s26
	v_lshl_add_u64 v[210:211], s[16:17], 0, v[160:161]
	ds_read_b128 v[18:21], v184 offset:32768
	ds_read_b128 v[22:25], v184 offset:33792
	ds_read_b128 v[186:189], v184 offset:34816
	ds_read_b128 v[190:193], v184 offset:35840
	ds_read_b128 v[194:197], v184 offset:36864
	ds_read_b128 v[198:201], v184 offset:37888
	ds_read_b128 v[202:205], v184 offset:38912
	ds_read_b128 v[206:209], v184 offset:39936
	global_load_lds_dwordx4 v[210:211], off
	v_lshl_add_u64 v[210:211], s[16:17], 0, v[156:157]
	s_mov_b32 m0, s27
	s_nop 0
	global_load_lds_dwordx4 v[210:211], off
	s_waitcnt lgkmcnt(8)
	s_barrier
	s_waitcnt lgkmcnt(0)
	s_setprio 1
	s_waitcnt lgkmcnt(0)
	s_nop 1
	v_mfma_scale_f32_16x16x128_f8f6f4 v[150:153], v[2:9], v[18:25], v[150:153], v174, v174 op_sel_hi:[0,0,0]
	s_nop 1
	v_mfma_scale_f32_16x16x128_f8f6f4 v[146:149], v[10:17], v[18:25], v[146:149], v174, v174 op_sel_hi:[0,0,0]
	s_nop 1
	v_mfma_scale_f32_16x16x128_f8f6f4 v[134:137], v[2:9], v[186:193], v[134:137], v174, v174 op_sel_hi:[0,0,0]
	s_nop 1
	v_mfma_scale_f32_16x16x128_f8f6f4 v[130:133], v[10:17], v[186:193], v[130:133], v174, v174 op_sel_hi:[0,0,0]
	s_nop 1
	v_mfma_scale_f32_16x16x128_f8f6f4 v[118:121], v[2:9], v[194:201], v[118:121], v174, v174 op_sel_hi:[0,0,0]
	s_nop 1
	v_mfma_scale_f32_16x16x128_f8f6f4 v[114:117], v[10:17], v[194:201], v[114:117], v174, v174 op_sel_hi:[0,0,0]
	s_nop 1
	v_mfma_scale_f32_16x16x128_f8f6f4 v[102:105], v[2:9], v[202:209], v[102:105], v174, v174 op_sel_hi:[0,0,0]
	s_nop 1
	v_mfma_scale_f32_16x16x128_f8f6f4 v[98:101], v[10:17], v[202:209], v[98:101], v174, v174 op_sel_hi:[0,0,0]
	s_setprio 0
	s_barrier
	s_add_i32 s16, 0, 0x1c000
	s_add_i32 s17, s30, s23
	v_add_u32_e32 v0, s16, v183
	v_lshl_add_u64 v[166:167], v[166:167], 0, s[56:57]
	s_mov_b32 m0, s17
	ds_read_b128 v[210:213], v0
	ds_read_b128 v[214:217], v0 offset:1024
	ds_read_b128 v[236:239], v0 offset:2048
	ds_read_b128 v[240:243], v0 offset:3072
	global_load_lds_dwordx4 v[166:167], off
	v_lshl_add_u64 v[166:167], v[168:169], 0, s[56:57]
	s_add_i32 m0, s17, 0x2000
	s_nop 0
	global_load_lds_dwordx4 v[166:167], off
	s_barrier
	s_waitcnt lgkmcnt(0)
	s_setprio 1
	s_waitcnt lgkmcnt(0)
	s_nop 1
	v_mfma_scale_f32_16x16x128_f8f6f4 v[142:145], v[210:217], v[18:25], v[142:145], v174, v174 op_sel_hi:[0,0,0]
	s_nop 1
	v_mfma_scale_f32_16x16x128_f8f6f4 v[138:141], v[236:243], v[18:25], v[138:141], v174, v174 op_sel_hi:[0,0,0]
	s_nop 1
	v_mfma_scale_f32_16x16x128_f8f6f4 v[126:129], v[210:217], v[186:193], v[126:129], v174, v174 op_sel_hi:[0,0,0]
	s_nop 1
	v_mfma_scale_f32_16x16x128_f8f6f4 v[122:125], v[236:243], v[186:193], v[122:125], v174, v174 op_sel_hi:[0,0,0]
	s_nop 1
	v_mfma_scale_f32_16x16x128_f8f6f4 v[110:113], v[210:217], v[194:201], v[110:113], v174, v174 op_sel_hi:[0,0,0]
	s_nop 1
	v_mfma_scale_f32_16x16x128_f8f6f4 v[106:109], v[236:243], v[194:201], v[106:109], v174, v174 op_sel_hi:[0,0,0]
	s_nop 1
	v_mfma_scale_f32_16x16x128_f8f6f4 v[94:97], v[210:217], v[202:209], v[94:97], v174, v174 op_sel_hi:[0,0,0]
	s_nop 1
	v_mfma_scale_f32_16x16x128_f8f6f4 v[90:93], v[236:243], v[202:209], v[90:93], v174, v174 op_sel_hi:[0,0,0]
	s_setprio 0
	s_mov_b32 m0, s54
	v_lshl_add_u64 v[166:167], v[170:171], 0, s[56:57]
	s_barrier
	ds_read_b128 v[18:21], v184 offset:49152
	ds_read_b128 v[22:25], v184 offset:50176
	ds_read_b128 v[186:189], v184 offset:51200
	ds_read_b128 v[190:193], v184 offset:52224
	ds_read_b128 v[194:197], v184 offset:53248
	ds_read_b128 v[198:201], v184 offset:54272
	ds_read_b128 v[202:205], v184 offset:55296
	ds_read_b128 v[206:209], v184 offset:56320
	global_load_lds_dwordx4 v[166:167], off
	v_lshl_add_u64 v[166:167], v[172:173], 0, s[56:57]
	s_mov_b32 m0, s66
	s_nop 0
	global_load_lds_dwordx4 v[166:167], off
	s_barrier
	s_waitcnt lgkmcnt(0)
	s_setprio 1
	s_waitcnt lgkmcnt(0)
	s_nop 1
	v_mfma_scale_f32_16x16x128_f8f6f4 v[86:89], v[2:9], v[18:25], v[86:89], v174, v174 op_sel_hi:[0,0,0]
	s_nop 1
	v_mfma_scale_f32_16x16x128_f8f6f4 v[82:85], v[10:17], v[18:25], v[82:85], v174, v174 op_sel_hi:[0,0,0]
	s_nop 1
	v_mfma_scale_f32_16x16x128_f8f6f4 v[70:73], v[2:9], v[186:193], v[70:73], v174, v174 op_sel_hi:[0,0,0]
	s_nop 1
	v_mfma_scale_f32_16x16x128_f8f6f4 v[66:69], v[10:17], v[186:193], v[66:69], v174, v174 op_sel_hi:[0,0,0]
	s_nop 1
	v_mfma_scale_f32_16x16x128_f8f6f4 v[54:57], v[2:9], v[194:201], v[54:57], v174, v174 op_sel_hi:[0,0,0]
	s_nop 1
	v_mfma_scale_f32_16x16x128_f8f6f4 v[50:53], v[10:17], v[194:201], v[50:53], v174, v174 op_sel_hi:[0,0,0]
	s_nop 1
	v_mfma_scale_f32_16x16x128_f8f6f4 v[38:41], v[2:9], v[202:209], v[38:41], v174, v174 op_sel_hi:[0,0,0]
	s_nop 1
	v_mfma_scale_f32_16x16x128_f8f6f4 v[34:37], v[10:17], v[202:209], v[34:37], v174, v174 op_sel_hi:[0,0,0]
	s_setprio 0
	s_barrier
; #define PG8_STAGE(bufoff, gbase, voff) do { _Pragma("unroll") for (int _i = 0; _i < 2; ++_i) \
;         __builtin_amdgcn_global_load_lds((const unsigned*)((const char*)(gbase) + (voff)[_i]), (PG8_LAS unsigned*)(lds + (bufoff) + ldsw + _i * 8192), 16, 0, 0); } while (0)
; #define PG8_WAIT_V(n) asm volatile("s_waitcnt vmcnt(" #n ")" ::: "memory")
; #define PG8_BAR __builtin_amdgcn_s_barrier()
; template <bool FP8, class Epi, class Sched>
; __device__ __forceinline__ void gemm_phase(PG8_LAS unsigned char* lds, const Gemm g, const Sched& S, const Epi& E) {
;     ...
;             PG8_STAGE(PG8_SB(1, 1), b3 + hstep, voffB);
;             PG8_WAIT_V(6); PG8_BAR; PG8_MMA(1, 1, At, B1); PG8_BAR;
;         }
;   DI void operator()(const f32x4 (&acc)[2][2][4][2], const pg8::Unit& u, int wr, int wc, int fr, int fq) const {
;     const int row0 = u.pm * 256 + wr * 64 + fr, colb = u.pn * 256 + wc * 32 + 8 * fq;
; #pragma unroll
;     for (int ai = 0; ai < 2; ++ai)
; #pragma unroll
;       for (int m = 0; m < 4; ++m) {
;         const int row = row0 + ai * 128 + m * 16;
; #pragma unroll
;         for (int bj = 0; bj < 2; ++bj) {
;           const int col = colb + bj * 128;
;           f32x4 v0 = acc[ai][bj][m][0] * sc, v1 = acc[ai][bj][m][1] * sc;
;           u16* dst = nullptr;
;           if (MODE == 0) { if (col < N) dst = d0 + (size_t)row * ld0 + (col + coff2 + ((col < csplit) ? (coff1 - coff2) : 0)); }
;           else if (MODE == 1) {
;             const int oc = col + coff2 + ((col < csplit) ? (coff1 - coff2) : 0);
;             if (col < N) {
;               if (oc < 2048) dst = d0 + (size_t)row * 2048 + oc;
;               else if (oc < 2112) { rot(v0, v1, row, oc); dst = d2 + (size_t)row * 64 + (oc - 2048); }
;               else dst = d1 + (size_t)row * 4096 + (oc - 2112);
;             }
;           } else if (MODE == 3) {
;             if (col < N) { const bool lo = col < csplit; u16* bp = lo ? d0 : d1; const int ldd = lo ? 2048 : 4096, oc = lo ? col : col + (coff2 - 2112); dst = bp + (size_t)row * ldd + oc + (lo ? coff1 : 0); }
;           } else {
;             if (((col >> 6) % 3) == 2) rot(v0, v1, row, col);
;             dst = d0 + (size_t)row * 3072 + col;
;           }
;           if (dst) { u32x4 w = {pk2(v0[0], v0[1]), pk2(v0[2], v0[3]), pk2(v1[0], v1[1]), pk2(v1[2], v1[3])}; *(u32x4*)dst = w; }
	s_add_u32 s12, s12, 0x30080
	s_addc_u32 s13, s13, 0
	s_add_i32 s16, s16, s23
	v_lshl_add_u64 v[2:3], s[12:13], 0, v[158:159]
	s_mov_b32 m0, s16
	s_nop 0
	global_load_lds_dwordx4 v[2:3], off
	v_lshl_add_u64 v[2:3], s[12:13], 0, v[154:155]
	s_add_i32 m0, s16, 0x2000
	s_nop 0
	global_load_lds_dwordx4 v[2:3], off
	s_waitcnt vmcnt(6)
	s_barrier
	s_setprio 1
	s_nop 1
	v_mfma_scale_f32_16x16x128_f8f6f4 v[78:81], v[210:217], v[18:25], v[78:81], v174, v174 op_sel_hi:[0,0,0]
	s_nop 1
	v_mfma_scale_f32_16x16x128_f8f6f4 v[74:77], v[236:243], v[18:25], v[74:77], v174, v174 op_sel_hi:[0,0,0]
	s_nop 1
	v_mfma_scale_f32_16x16x128_f8f6f4 v[62:65], v[210:217], v[186:193], v[62:65], v174, v174 op_sel_hi:[0,0,0]
	s_nop 1
	v_mfma_scale_f32_16x16x128_f8f6f4 v[58:61], v[236:243], v[186:193], v[58:61], v174, v174 op_sel_hi:[0,0,0]
	s_nop 1
	v_mfma_scale_f32_16x16x128_f8f6f4 v[46:49], v[210:217], v[194:201], v[46:49], v174, v174 op_sel_hi:[0,0,0]
	s_nop 1
	v_mfma_scale_f32_16x16x128_f8f6f4 v[42:45], v[236:243], v[194:201], v[42:45], v174, v174 op_sel_hi:[0,0,0]
	s_nop 1
	v_mfma_scale_f32_16x16x128_f8f6f4 v[30:33], v[210:217], v[202:209], v[30:33], v174, v174 op_sel_hi:[0,0,0]
	s_nop 1
	v_mfma_scale_f32_16x16x128_f8f6f4 v[26:29], v[236:243], v[202:209], v[26:29], v174, v174 op_sel_hi:[0,0,0]
	s_setprio 0
	s_add_i32 s73, s73, 2
	s_add_u32 s71, s71, 0x100
	s_addc_u32 s72, s72, 0
	s_cmp_gt_u32 s73, 9
	s_mov_b64 s[16:17], s[10:11]
	s_barrier
	s_cbranch_scc0 .LBB0_1090
	s_lshl_b32 s10, s28, 8
	s_or_b32 s10, s10, s67
	v_or_b32_e32 v4, s10, v182
	s_ashr_i32 s10, s10, 6
	s_mul_hi_i32 s11, s10, 0x55555556
	s_lshr_b32 s12, s11, 31
	s_add_i32 s11, s11, s12
	v_lshl_add_u32 v16, s29, 8, v175
	v_lshrrev_b32_e32 v0, 1, v4
	s_mul_i32 s11, s11, 3
	s_nop 15
	s_nop 15
	v_and_b32_e32 v2, 28, v0
	v_lshlrev_b32_e32 v0, 5, v16
	s_sub_i32 s10, s10, s11
	v_and_b32_e32 v0, 0xf9e0, v0
	s_cmp_eq_u32 s10, 2
	v_pk_mul_f32 v[14:15], v[152:153], s[58:59] op_sel_hi:[1,0]
	v_pk_mul_f32 v[8:9], v[150:151], s[58:59] op_sel_hi:[1,0]
	v_pk_mul_f32 v[12:13], v[148:149], s[58:59] op_sel_hi:[1,0]
	v_pk_mul_f32 v[10:11], v[146:147], s[58:59] op_sel_hi:[1,0]
	s_cselect_b64 s[16:17], -1, 0
	s_cmp_lg_u32 s10, 2
	v_lshlrev_b32_e32 v0, 3, v0
	v_lshlrev_b32_e32 v2, 3, v2
	v_mov_b32_e32 v238, v2
	v_mov_b32_e32 v239, 0
	v_mov_b32_e32 v236, v16
	v_lshlrev_b32_e32 v236, 5, v236
	v_and_b32_e32 v236, 0xffe0, v236
	v_lshlrev_b32_e32 v236, 3, v236
	v_mov_b32_e32 v237, 0
	v_lshl_add_u64 v[236:237], s[52:53], 0, v[236:237]
	v_lshl_add_u64 v[236:237], v[236:237], 0, v[238:239]
	global_load_dwordx4 v[186:189], v[236:237], off offset:16
	global_load_dwordx4 v[190:193], v[236:237], off
	v_add_u32_e32 v236, 16, v16
	v_lshlrev_b32_e32 v236, 5, v236
	v_and_b32_e32 v236, 0xffe0, v236
	v_lshlrev_b32_e32 v236, 3, v236
	v_mov_b32_e32 v237, 0
	v_lshl_add_u64 v[236:237], s[52:53], 0, v[236:237]
	v_lshl_add_u64 v[236:237], v[236:237], 0, v[238:239]
	global_load_dwordx4 v[194:197], v[236:237], off offset:16
	global_load_dwordx4 v[198:201], v[236:237], off
	v_add_u32_e32 v236, 32, v16
	v_lshlrev_b32_e32 v236, 5, v236
	v_and_b32_e32 v236, 0xffe0, v236
	v_lshlrev_b32_e32 v236, 3, v236
	v_mov_b32_e32 v237, 0
	v_lshl_add_u64 v[236:237], s[52:53], 0, v[236:237]
	v_lshl_add_u64 v[236:237], v[236:237], 0, v[238:239]
	global_load_dwordx4 v[202:205], v[236:237], off offset:16
	global_load_dwordx4 v[206:209], v[236:237], off
	v_add_u32_e32 v236, 48, v16
	v_lshlrev_b32_e32 v236, 5, v236
	v_and_b32_e32 v236, 0xffe0, v236
	v_lshlrev_b32_e32 v236, 3, v236
	v_mov_b32_e32 v237, 0
	v_lshl_add_u64 v[236:237], s[52:53], 0, v[236:237]
	v_lshl_add_u64 v[236:237], v[236:237], 0, v[238:239]
	global_load_dwordx4 v[210:213], v[236:237], off offset:16
	global_load_dwordx4 v[214:217], v[236:237], off
	s_waitcnt vmcnt(0)
	s_cbranch_scc1 .LBB0_1093
	v_mov_b32_e32 v3, v1
	v_mov_b32_e32 v18, v186
	v_mov_b32_e32 v19, v187
	v_mov_b32_e32 v20, v188
	v_mov_b32_e32 v21, v189
	v_mov_b32_e32 v22, v190
	v_mov_b32_e32 v23, v191
	v_mov_b32_e32 v24, v192
	v_mov_b32_e32 v25, v193
	v_pk_mul_f32 v[148:149], v[10:11], v[18:19] op_sel:[1,1] op_sel_hi:[0,1]
	v_pk_mul_f32 v[146:147], v[8:9], v[22:23] op_sel:[1,1] op_sel_hi:[0,1]
	v_pk_mul_f32 v[6:7], v[8:9], v[22:23]
	v_pk_fma_f32 v[8:9], v[8:9], v[22:23], v[146:147] op_sel_hi:[1,0,1]
	s_nop 0
	v_mul_f32_e32 v8, v15, v25
	v_pk_fma_f32 v[22:23], v[14:15], v[24:25], v[8:9] op_sel_hi:[1,1,0] neg_lo:[0,0,1] neg_hi:[0,0,1]
	v_mul_f32_e32 v8, v14, v25
	v_pk_fma_f32 v[24:25], v[14:15], v[24:25], v[8:9] op_sel:[1,0,0] op_sel_hi:[0,1,0]
	v_mul_f32_e32 v8, v13, v21
	v_pk_mul_f32 v[14:15], v[10:11], v[18:19]
	v_pk_fma_f32 v[10:11], v[10:11], v[18:19], v[148:149] op_sel_hi:[1,0,1]
	v_pk_fma_f32 v[18:19], v[12:13], v[20:21], v[8:9] op_sel_hi:[1,1,0] neg_lo:[0,0,1] neg_hi:[0,0,1]
	v_mul_f32_e32 v8, v12, v21
	v_pk_fma_f32 v[20:21], v[12:13], v[20:21], v[8:9] op_sel:[1,0,0] op_sel_hi:[0,1,0]
	v_sub_f32_e32 v10, v14, v148
	v_sub_f32_e32 v8, v6, v146
	v_mov_b32_e32 v12, v18
	v_mov_b32_e32 v13, v20
	v_mov_b32_e32 v14, v22
	v_mov_b32_e32 v15, v24
;   DI void operator()(const f32x4 (&acc)[2][2][4][2], const pg8::Unit& u, int wr, int wc, int fr, int fq) const {
;     const int row0 = u.pm * 256 + wr * 64 + fr, colb = u.pn * 256 + wc * 32 + 8 * fq;
; #pragma unroll
;     for (int ai = 0; ai < 2; ++ai)
; #pragma unroll
;       for (int m = 0; m < 4; ++m) {
;         const int row = row0 + ai * 128 + m * 16;
; #pragma unroll
;         for (int bj = 0; bj < 2; ++bj) {
;           const int col = colb + bj * 128;
;           f32x4 v0 = acc[ai][bj][m][0] * sc, v1 = acc[ai][bj][m][1] * sc;
;           u16* dst = nullptr;
;           if (MODE == 0) { if (col < N) dst = d0 + (size_t)row * ld0 + (col + coff2 + ((col < csplit) ? (coff1 - coff2) : 0)); }
;           else if (MODE == 1) {
;             const int oc = col + coff2 + ((col < csplit) ? (coff1 - coff2) : 0);
;             if (col < N) {
;               if (oc < 2048) dst = d0 + (size_t)row * 2048 + oc;
;               else if (oc < 2112) { rot(v0, v1, row, oc); dst = d2 + (size_t)row * 64 + (oc - 2048); }
;               else dst = d1 + (size_t)row * 4096 + (oc - 2112);
;             }
;           } else if (MODE == 3) {
;             if (col < N) { const bool lo = col < csplit; u16* bp = lo ? d0 : d1; const int ldd = lo ? 2048 : 4096, oc = lo ? col : col + (coff2 - 2112); dst = bp + (size_t)row * ldd + oc + (lo ? coff1 : 0); }
;           } else {
;             if (((col >> 6) % 3) == 2) rot(v0, v1, row, col);
;             dst = d0 + (size_t)row * 3072 + col;
;           }
;           if (dst) { u32x4 w = {pk2(v0[0], v0[1]), pk2(v0[2], v0[3]), pk2(v1[0], v1[1]), pk2(v1[2], v1[3])}; *(u32x4*)dst = w; }
.LBB0_1093:
	v_mov_b64_e32 v[6:7], s[74:75]
	s_movk_i32 s10, 0x1800
	v_mad_i64_i32 v[6:7], s[10:11], v16, s10, v[6:7]
	v_ashrrev_i32_e32 v3, 6, v4
	v_or_b32_e32 v3, 2, v3
	s_mov_b32 s10, 0x55555556
	v_mul_hi_i32 v17, v3, s10
	v_lshrrev_b32_e32 v18, 31, v17
	v_add_u32_e32 v17, v17, v18
	v_ashrrev_i32_e32 v5, 31, v4
	v_lshl_add_u32 v17, v17, 1, v17
	v_lshl_add_u64 v[6:7], v[4:5], 1, v[6:7]
	v_cvt_pk_bf16_f32 v8, v8, v9
	v_cvt_pk_bf16_f32 v9, v14, v15
	v_cvt_pk_bf16_f32 v10, v10, v11
	v_cvt_pk_bf16_f32 v11, v12, v13
	v_sub_u32_e32 v3, v3, v17
	global_store_dwordx4 v[6:7], v[8:11], off
	v_pk_mul_f32 v[14:15], v[144:145], s[58:59] op_sel_hi:[1,0]
	v_pk_mul_f32 v[12:13], v[140:141], s[58:59] op_sel_hi:[1,0]
	v_pk_mul_f32 v[8:9], v[142:143], s[58:59] op_sel_hi:[1,0]
	v_pk_mul_f32 v[10:11], v[138:139], s[58:59] op_sel_hi:[1,0]
	v_cmp_eq_u32_e64 s[10:11], 2, v3
	s_and_saveexec_b64 s[12:13], s[10:11]
	s_cbranch_execz .LBB0_1095
	v_mov_b32_e32 v3, v1
	v_mov_b32_e32 v18, v186
	v_mov_b32_e32 v19, v187
	v_mov_b32_e32 v20, v188
	v_mov_b32_e32 v21, v189
	v_mov_b32_e32 v22, v190
	v_mov_b32_e32 v23, v191
	v_mov_b32_e32 v24, v192
	v_mov_b32_e32 v25, v193
	v_pk_mul_f32 v[142:143], v[10:11], v[18:19] op_sel:[1,1] op_sel_hi:[0,1]
	v_pk_mul_f32 v[140:141], v[8:9], v[22:23] op_sel:[1,1] op_sel_hi:[0,1]
	v_mul_f32_e32 v0, v15, v25
	v_pk_mul_f32 v[138:139], v[8:9], v[22:23]
	v_pk_fma_f32 v[8:9], v[8:9], v[22:23], v[140:141] op_sel_hi:[1,0,1]
	v_pk_fma_f32 v[22:23], v[14:15], v[24:25], v[0:1] op_sel_hi:[1,1,0] neg_lo:[0,0,1] neg_hi:[0,0,1]
	v_mul_f32_e32 v0, v14, v25
	v_pk_fma_f32 v[24:25], v[14:15], v[24:25], v[0:1] op_sel:[1,0,0] op_sel_hi:[0,1,0]
	v_mul_f32_e32 v0, v13, v21
	v_pk_mul_f32 v[14:15], v[10:11], v[18:19]
	v_pk_fma_f32 v[10:11], v[10:11], v[18:19], v[142:143] op_sel_hi:[1,0,1]
	v_pk_fma_f32 v[18:19], v[12:13], v[20:21], v[0:1] op_sel_hi:[1,1,0] neg_lo:[0,0,1] neg_hi:[0,0,1]
	v_mul_f32_e32 v0, v12, v21
	v_pk_fma_f32 v[20:21], v[12:13], v[20:21], v[0:1] op_sel:[1,0,0] op_sel_hi:[0,1,0]
	v_sub_f32_e32 v10, v14, v142
	v_sub_f32_e32 v8, v138, v140
	v_mov_b32_e32 v12, v18
	v_mov_b32_e32 v13, v20
	v_mov_b32_e32 v14, v22
	v_mov_b32_e32 v15, v24
.LBB0_1095:
	s_or_b64 exec, exec, s[12:13]
	v_cvt_pk_bf16_f32 v8, v8, v9
	v_cvt_pk_bf16_f32 v9, v14, v15
	v_cvt_pk_bf16_f32 v10, v10, v11
	v_cvt_pk_bf16_f32 v11, v12, v13
	global_store_dwordx4 v[6:7], v[8:11], off offset:256
	v_or_b32_e32 v6, 16, v16
	v_lshlrev_b32_e32 v0, 5, v6
	v_and_b32_e32 v0, 0xfbe0, v0
	v_cndmask_b32_e64 v3, 0, 1, s[16:17]
	v_pk_mul_f32 v[14:15], v[136:137], s[58:59] op_sel_hi:[1,0]
	v_pk_mul_f32 v[8:9], v[134:135], s[58:59] op_sel_hi:[1,0]
	v_pk_mul_f32 v[12:13], v[132:133], s[58:59] op_sel_hi:[1,0]
	v_pk_mul_f32 v[10:11], v[130:131], s[58:59] op_sel_hi:[1,0]
	v_cmp_ne_u32_e64 s[12:13], 1, v3
	s_andn2_b64 vcc, exec, s[16:17]
	v_lshlrev_b32_e32 v0, 3, v0
	s_cbranch_vccnz .LBB0_1097
	v_mov_b32_e32 v3, v1
	v_mov_b32_e32 v18, v194
	v_mov_b32_e32 v19, v195
	v_mov_b32_e32 v20, v196
	v_mov_b32_e32 v21, v197
	v_mov_b32_e32 v22, v198
	v_mov_b32_e32 v23, v199
	v_mov_b32_e32 v24, v200
	v_mov_b32_e32 v25, v201
	v_pk_mul_f32 v[134:135], v[10:11], v[18:19] op_sel:[1,1] op_sel_hi:[0,1]
	v_pk_mul_f32 v[132:133], v[8:9], v[22:23] op_sel:[1,1] op_sel_hi:[0,1]
	v_pk_mul_f32 v[130:131], v[8:9], v[22:23]
	v_pk_fma_f32 v[8:9], v[8:9], v[22:23], v[132:133] op_sel_hi:[1,0,1]
	s_nop 0
	v_mul_f32_e32 v8, v15, v25
	v_pk_fma_f32 v[22:23], v[14:15], v[24:25], v[8:9] op_sel_hi:[1,1,0] neg_lo:[0,0,1] neg_hi:[0,0,1]
	v_mul_f32_e32 v8, v14, v25
	v_pk_fma_f32 v[24:25], v[14:15], v[24:25], v[8:9] op_sel:[1,0,0] op_sel_hi:[0,1,0]
	v_mul_f32_e32 v8, v13, v21
	v_pk_mul_f32 v[14:15], v[10:11], v[18:19]
	v_pk_fma_f32 v[10:11], v[10:11], v[18:19], v[134:135] op_sel_hi:[1,0,1]
	v_pk_fma_f32 v[18:19], v[12:13], v[20:21], v[8:9] op_sel_hi:[1,1,0] neg_lo:[0,0,1] neg_hi:[0,0,1]
	v_mul_f32_e32 v8, v12, v21
	v_pk_fma_f32 v[20:21], v[12:13], v[20:21], v[8:9] op_sel:[1,0,0] op_sel_hi:[0,1,0]
	v_sub_f32_e32 v10, v14, v134
	v_sub_f32_e32 v8, v130, v132
	v_mov_b32_e32 v12, v18
	v_mov_b32_e32 v13, v20
	v_mov_b32_e32 v14, v22
	v_mov_b32_e32 v15, v24
.LBB0_1097:
	v_mov_b64_e32 v[18:19], s[74:75]
	s_movk_i32 s16, 0x1800
	v_mad_i64_i32 v[6:7], s[16:17], v6, s16, v[18:19]
	v_lshl_add_u64 v[6:7], v[4:5], 1, v[6:7]
	v_cvt_pk_bf16_f32 v8, v8, v9
	v_cvt_pk_bf16_f32 v9, v14, v15
	v_cvt_pk_bf16_f32 v10, v10, v11
	v_cvt_pk_bf16_f32 v11, v12, v13
	global_store_dwordx4 v[6:7], v[8:11], off
	v_pk_mul_f32 v[14:15], v[128:129], s[58:59] op_sel_hi:[1,0]
	v_pk_mul_f32 v[12:13], v[124:125], s[58:59] op_sel_hi:[1,0]
	v_pk_mul_f32 v[8:9], v[126:127], s[58:59] op_sel_hi:[1,0]
	v_pk_mul_f32 v[10:11], v[122:123], s[58:59] op_sel_hi:[1,0]
	s_and_saveexec_b64 s[16:17], s[10:11]
	s_cbranch_execz .LBB0_1099
	v_mov_b32_e32 v3, v1
	v_mov_b32_e32 v18, v194
	v_mov_b32_e32 v19, v195
	v_mov_b32_e32 v20, v196
	v_mov_b32_e32 v21, v197
	v_mov_b32_e32 v22, v198
	v_mov_b32_e32 v23, v199
	v_mov_b32_e32 v24, v200
	v_mov_b32_e32 v25, v201
	v_pk_mul_f32 v[126:127], v[10:11], v[18:19] op_sel:[1,1] op_sel_hi:[0,1]
	v_pk_mul_f32 v[124:125], v[8:9], v[22:23] op_sel:[1,1] op_sel_hi:[0,1]
	v_mul_f32_e32 v0, v15, v25
	v_pk_mul_f32 v[122:123], v[8:9], v[22:23]
	v_pk_fma_f32 v[8:9], v[8:9], v[22:23], v[124:125] op_sel_hi:[1,0,1]
	v_pk_fma_f32 v[22:23], v[14:15], v[24:25], v[0:1] op_sel_hi:[1,1,0] neg_lo:[0,0,1] neg_hi:[0,0,1]
	v_mul_f32_e32 v0, v14, v25
	v_pk_fma_f32 v[24:25], v[14:15], v[24:25], v[0:1] op_sel:[1,0,0] op_sel_hi:[0,1,0]
	v_mul_f32_e32 v0, v13, v21
	v_pk_mul_f32 v[14:15], v[10:11], v[18:19]
	v_pk_fma_f32 v[10:11], v[10:11], v[18:19], v[126:127] op_sel_hi:[1,0,1]
	v_pk_fma_f32 v[18:19], v[12:13], v[20:21], v[0:1] op_sel_hi:[1,1,0] neg_lo:[0,0,1] neg_hi:[0,0,1]
	v_mul_f32_e32 v0, v12, v21
	v_pk_fma_f32 v[20:21], v[12:13], v[20:21], v[0:1] op_sel:[1,0,0] op_sel_hi:[0,1,0]
	v_sub_f32_e32 v10, v14, v126
	v_sub_f32_e32 v8, v122, v124
	v_mov_b32_e32 v12, v18
	v_mov_b32_e32 v13, v20
	v_mov_b32_e32 v14, v22
	v_mov_b32_e32 v15, v24
;   DI void operator()(const f32x4 (&acc)[2][2][4][2], const pg8::Unit& u, int wr, int wc, int fr, int fq) const {
;     const int row0 = u.pm * 256 + wr * 64 + fr, colb = u.pn * 256 + wc * 32 + 8 * fq;
; #pragma unroll
;     for (int ai = 0; ai < 2; ++ai)
; #pragma unroll
;       for (int m = 0; m < 4; ++m) {
;         const int row = row0 + ai * 128 + m * 16;
; #pragma unroll
;         for (int bj = 0; bj < 2; ++bj) {
;           const int col = colb + bj * 128;
;           f32x4 v0 = acc[ai][bj][m][0] * sc, v1 = acc[ai][bj][m][1] * sc;
;           u16* dst = nullptr;
;           if (MODE == 0) { if (col < N) dst = d0 + (size_t)row * ld0 + (col + coff2 + ((col < csplit) ? (coff1 - coff2) : 0)); }
;           else if (MODE == 1) {
;             const int oc = col + coff2 + ((col < csplit) ? (coff1 - coff2) : 0);
;             if (col < N) {
;               if (oc < 2048) dst = d0 + (size_t)row * 2048 + oc;
;               else if (oc < 2112) { rot(v0, v1, row, oc); dst = d2 + (size_t)row * 64 + (oc - 2048); }
;               else dst = d1 + (size_t)row * 4096 + (oc - 2112);
;             }
;           } else if (MODE == 3) {
;             if (col < N) { const bool lo = col < csplit; u16* bp = lo ? d0 : d1; const int ldd = lo ? 2048 : 4096, oc = lo ? col : col + (coff2 - 2112); dst = bp + (size_t)row * ldd + oc + (lo ? coff1 : 0); }
;           } else {
;             if (((col >> 6) % 3) == 2) rot(v0, v1, row, col);
;             dst = d0 + (size_t)row * 3072 + col;
;           }
;           if (dst) { u32x4 w = {pk2(v0[0], v0[1]), pk2(v0[2], v0[3]), pk2(v1[0], v1[1]), pk2(v1[2], v1[3])}; *(u32x4*)dst = w; }
.LBB0_1099:
	s_or_b64 exec, exec, s[16:17]
	v_cvt_pk_bf16_f32 v8, v8, v9
	v_cvt_pk_bf16_f32 v9, v14, v15
	v_cvt_pk_bf16_f32 v10, v10, v11
	v_cvt_pk_bf16_f32 v11, v12, v13
	global_store_dwordx4 v[6:7], v[8:11], off offset:256
	v_or_b32_e32 v6, 32, v16
	v_lshlrev_b32_e32 v0, 5, v6
	v_and_b32_e32 v0, 0xfde0, v0
	v_pk_mul_f32 v[14:15], v[120:121], s[58:59] op_sel_hi:[1,0]
	v_pk_mul_f32 v[8:9], v[118:119], s[58:59] op_sel_hi:[1,0]
	v_pk_mul_f32 v[12:13], v[116:117], s[58:59] op_sel_hi:[1,0]
	v_pk_mul_f32 v[10:11], v[114:115], s[58:59] op_sel_hi:[1,0]
	s_and_b64 vcc, exec, s[12:13]
	v_lshlrev_b32_e32 v0, 3, v0
	s_cbranch_vccnz .LBB0_1101
	v_mov_b32_e32 v3, v1
	v_mov_b32_e32 v18, v202
	v_mov_b32_e32 v19, v203
	v_mov_b32_e32 v20, v204
	v_mov_b32_e32 v21, v205
	v_mov_b32_e32 v22, v206
	v_mov_b32_e32 v23, v207
	v_mov_b32_e32 v24, v208
	v_mov_b32_e32 v25, v209
	v_pk_mul_f32 v[118:119], v[10:11], v[18:19] op_sel:[1,1] op_sel_hi:[0,1]
	v_pk_mul_f32 v[116:117], v[8:9], v[22:23] op_sel:[1,1] op_sel_hi:[0,1]
	v_pk_mul_f32 v[114:115], v[8:9], v[22:23]
	v_pk_fma_f32 v[8:9], v[8:9], v[22:23], v[116:117] op_sel_hi:[1,0,1]
	s_nop 0
	v_mul_f32_e32 v8, v15, v25
	v_pk_fma_f32 v[22:23], v[14:15], v[24:25], v[8:9] op_sel_hi:[1,1,0] neg_lo:[0,0,1] neg_hi:[0,0,1]
	v_mul_f32_e32 v8, v14, v25
	v_pk_fma_f32 v[24:25], v[14:15], v[24:25], v[8:9] op_sel:[1,0,0] op_sel_hi:[0,1,0]
	v_mul_f32_e32 v8, v13, v21
	v_pk_mul_f32 v[14:15], v[10:11], v[18:19]
	v_pk_fma_f32 v[10:11], v[10:11], v[18:19], v[118:119] op_sel_hi:[1,0,1]
	v_pk_fma_f32 v[18:19], v[12:13], v[20:21], v[8:9] op_sel_hi:[1,1,0] neg_lo:[0,0,1] neg_hi:[0,0,1]
	v_mul_f32_e32 v8, v12, v21
	v_pk_fma_f32 v[20:21], v[12:13], v[20:21], v[8:9] op_sel:[1,0,0] op_sel_hi:[0,1,0]
	v_sub_f32_e32 v10, v14, v118
	v_sub_f32_e32 v8, v114, v116
	v_mov_b32_e32 v12, v18
	v_mov_b32_e32 v13, v20
	v_mov_b32_e32 v14, v22
	v_mov_b32_e32 v15, v24
.LBB0_1101:
	v_mov_b64_e32 v[18:19], s[74:75]
	s_movk_i32 s16, 0x1800
	v_mad_i64_i32 v[6:7], s[16:17], v6, s16, v[18:19]
	v_lshl_add_u64 v[6:7], v[4:5], 1, v[6:7]
	v_cvt_pk_bf16_f32 v8, v8, v9
	v_cvt_pk_bf16_f32 v9, v14, v15
	v_cvt_pk_bf16_f32 v10, v10, v11
	v_cvt_pk_bf16_f32 v11, v12, v13
	global_store_dwordx4 v[6:7], v[8:11], off
	v_pk_mul_f32 v[14:15], v[112:113], s[58:59] op_sel_hi:[1,0]
	v_pk_mul_f32 v[12:13], v[108:109], s[58:59] op_sel_hi:[1,0]
	v_pk_mul_f32 v[8:9], v[110:111], s[58:59] op_sel_hi:[1,0]
	v_pk_mul_f32 v[10:11], v[106:107], s[58:59] op_sel_hi:[1,0]
	s_and_saveexec_b64 s[16:17], s[10:11]
	s_cbranch_execz .LBB0_1103
	v_mov_b32_e32 v3, v1
	v_mov_b32_e32 v18, v202
	v_mov_b32_e32 v19, v203
	v_mov_b32_e32 v20, v204
	v_mov_b32_e32 v21, v205
	v_mov_b32_e32 v22, v206
	v_mov_b32_e32 v23, v207
	v_mov_b32_e32 v24, v208
	v_mov_b32_e32 v25, v209
	v_pk_mul_f32 v[110:111], v[10:11], v[18:19] op_sel:[1,1] op_sel_hi:[0,1]
	v_pk_mul_f32 v[108:109], v[8:9], v[22:23] op_sel:[1,1] op_sel_hi:[0,1]
	v_mul_f32_e32 v0, v15, v25
	v_pk_mul_f32 v[106:107], v[8:9], v[22:23]
	v_pk_fma_f32 v[8:9], v[8:9], v[22:23], v[108:109] op_sel_hi:[1,0,1]
	v_pk_fma_f32 v[22:23], v[14:15], v[24:25], v[0:1] op_sel_hi:[1,1,0] neg_lo:[0,0,1] neg_hi:[0,0,1]
	v_mul_f32_e32 v0, v14, v25
	v_pk_fma_f32 v[24:25], v[14:15], v[24:25], v[0:1] op_sel:[1,0,0] op_sel_hi:[0,1,0]
	v_mul_f32_e32 v0, v13, v21
	v_pk_mul_f32 v[14:15], v[10:11], v[18:19]
	v_pk_fma_f32 v[10:11], v[10:11], v[18:19], v[110:111] op_sel_hi:[1,0,1]
	v_pk_fma_f32 v[18:19], v[12:13], v[20:21], v[0:1] op_sel_hi:[1,1,0] neg_lo:[0,0,1] neg_hi:[0,0,1]
	v_mul_f32_e32 v0, v12, v21
	v_pk_fma_f32 v[20:21], v[12:13], v[20:21], v[0:1] op_sel:[1,0,0] op_sel_hi:[0,1,0]
	v_sub_f32_e32 v10, v14, v110
	v_sub_f32_e32 v8, v106, v108
	v_mov_b32_e32 v12, v18
	v_mov_b32_e32 v13, v20
	v_mov_b32_e32 v14, v22
	v_mov_b32_e32 v15, v24
.LBB0_1103:
	s_or_b64 exec, exec, s[16:17]
	v_cvt_pk_bf16_f32 v8, v8, v9
	v_cvt_pk_bf16_f32 v9, v14, v15
	v_cvt_pk_bf16_f32 v10, v10, v11
	v_cvt_pk_bf16_f32 v11, v12, v13
	global_store_dwordx4 v[6:7], v[8:11], off offset:256
	v_or_b32_e32 v6, 48, v16
	v_lshlrev_b32_e32 v0, 5, v6
	v_and_b32_e32 v0, 0xffe0, v0
	v_pk_mul_f32 v[14:15], v[104:105], s[58:59] op_sel_hi:[1,0]
	v_pk_mul_f32 v[8:9], v[102:103], s[58:59] op_sel_hi:[1,0]
	v_pk_mul_f32 v[12:13], v[100:101], s[58:59] op_sel_hi:[1,0]
	v_pk_mul_f32 v[10:11], v[98:99], s[58:59] op_sel_hi:[1,0]
	s_and_b64 vcc, exec, s[12:13]
	v_lshlrev_b32_e32 v0, 3, v0
	s_cbranch_vccnz .LBB0_1105
	v_mov_b32_e32 v3, v1
	v_mov_b32_e32 v18, v210
	v_mov_b32_e32 v19, v211
	v_mov_b32_e32 v20, v212
	v_mov_b32_e32 v21, v213
	v_mov_b32_e32 v22, v214
	v_mov_b32_e32 v23, v215
	v_mov_b32_e32 v24, v216
	v_mov_b32_e32 v25, v217
	v_pk_mul_f32 v[102:103], v[10:11], v[18:19] op_sel:[1,1] op_sel_hi:[0,1]
	v_pk_mul_f32 v[100:101], v[8:9], v[22:23] op_sel:[1,1] op_sel_hi:[0,1]
	v_pk_mul_f32 v[98:99], v[8:9], v[22:23]
	v_pk_fma_f32 v[8:9], v[8:9], v[22:23], v[100:101] op_sel_hi:[1,0,1]
	s_nop 0
	v_mul_f32_e32 v8, v15, v25
	v_pk_fma_f32 v[22:23], v[14:15], v[24:25], v[8:9] op_sel_hi:[1,1,0] neg_lo:[0,0,1] neg_hi:[0,0,1]
	v_mul_f32_e32 v8, v14, v25
	v_pk_fma_f32 v[24:25], v[14:15], v[24:25], v[8:9] op_sel:[1,0,0] op_sel_hi:[0,1,0]
	v_mul_f32_e32 v8, v13, v21
	v_pk_mul_f32 v[14:15], v[10:11], v[18:19]
	v_pk_fma_f32 v[10:11], v[10:11], v[18:19], v[102:103] op_sel_hi:[1,0,1]
	v_pk_fma_f32 v[18:19], v[12:13], v[20:21], v[8:9] op_sel_hi:[1,1,0] neg_lo:[0,0,1] neg_hi:[0,0,1]
	v_mul_f32_e32 v8, v12, v21
	v_pk_fma_f32 v[20:21], v[12:13], v[20:21], v[8:9] op_sel:[1,0,0] op_sel_hi:[0,1,0]
	v_sub_f32_e32 v10, v14, v102
	v_sub_f32_e32 v8, v98, v100
	v_mov_b32_e32 v12, v18
	v_mov_b32_e32 v13, v20
	v_mov_b32_e32 v14, v22
	v_mov_b32_e32 v15, v24
;   DI void operator()(const f32x4 (&acc)[2][2][4][2], const pg8::Unit& u, int wr, int wc, int fr, int fq) const {
;     const int row0 = u.pm * 256 + wr * 64 + fr, colb = u.pn * 256 + wc * 32 + 8 * fq;
; #pragma unroll
;     for (int ai = 0; ai < 2; ++ai)
; #pragma unroll
;       for (int m = 0; m < 4; ++m) {
;         const int row = row0 + ai * 128 + m * 16;
; #pragma unroll
;         for (int bj = 0; bj < 2; ++bj) {
;           const int col = colb + bj * 128;
;           f32x4 v0 = acc[ai][bj][m][0] * sc, v1 = acc[ai][bj][m][1] * sc;
;           u16* dst = nullptr;
;           if (MODE == 0) { if (col < N) dst = d0 + (size_t)row * ld0 + (col + coff2 + ((col < csplit) ? (coff1 - coff2) : 0)); }
;           else if (MODE == 1) {
;             const int oc = col + coff2 + ((col < csplit) ? (coff1 - coff2) : 0);
;             if (col < N) {
;               if (oc < 2048) dst = d0 + (size_t)row * 2048 + oc;
;               else if (oc < 2112) { rot(v0, v1, row, oc); dst = d2 + (size_t)row * 64 + (oc - 2048); }
;               else dst = d1 + (size_t)row * 4096 + (oc - 2112);
;             }
;           } else if (MODE == 3) {
;             if (col < N) { const bool lo = col < csplit; u16* bp = lo ? d0 : d1; const int ldd = lo ? 2048 : 4096, oc = lo ? col : col + (coff2 - 2112); dst = bp + (size_t)row * ldd + oc + (lo ? coff1 : 0); }
;           } else {
;             if (((col >> 6) % 3) == 2) rot(v0, v1, row, col);
;             dst = d0 + (size_t)row * 3072 + col;
;           }
;           if (dst) { u32x4 w = {pk2(v0[0], v0[1]), pk2(v0[2], v0[3]), pk2(v1[0], v1[1]), pk2(v1[2], v1[3])}; *(u32x4*)dst = w; }
.LBB0_1105:
	v_mov_b64_e32 v[18:19], s[74:75]
	s_movk_i32 s16, 0x1800
	v_mad_i64_i32 v[6:7], s[16:17], v6, s16, v[18:19]
	v_lshl_add_u64 v[6:7], v[4:5], 1, v[6:7]
	v_cvt_pk_bf16_f32 v8, v8, v9
	v_cvt_pk_bf16_f32 v9, v14, v15
	v_cvt_pk_bf16_f32 v10, v10, v11
	v_cvt_pk_bf16_f32 v11, v12, v13
	global_store_dwordx4 v[6:7], v[8:11], off
	v_pk_mul_f32 v[14:15], v[96:97], s[58:59] op_sel_hi:[1,0]
	v_pk_mul_f32 v[12:13], v[92:93], s[58:59] op_sel_hi:[1,0]
	v_pk_mul_f32 v[8:9], v[94:95], s[58:59] op_sel_hi:[1,0]
	v_pk_mul_f32 v[10:11], v[90:91], s[58:59] op_sel_hi:[1,0]
	s_and_saveexec_b64 s[16:17], s[10:11]
	s_cbranch_execz .LBB0_1107
	v_mov_b32_e32 v3, v1
	v_mov_b32_e32 v18, v210
	v_mov_b32_e32 v19, v211
	v_mov_b32_e32 v20, v212
	v_mov_b32_e32 v21, v213
	v_mov_b32_e32 v22, v214
	v_mov_b32_e32 v23, v215
	v_mov_b32_e32 v24, v216
	v_mov_b32_e32 v25, v217
	v_pk_mul_f32 v[94:95], v[10:11], v[18:19] op_sel:[1,1] op_sel_hi:[0,1]
	v_pk_mul_f32 v[92:93], v[8:9], v[22:23] op_sel:[1,1] op_sel_hi:[0,1]
	v_mul_f32_e32 v0, v15, v25
	v_pk_mul_f32 v[90:91], v[8:9], v[22:23]
	v_pk_fma_f32 v[8:9], v[8:9], v[22:23], v[92:93] op_sel_hi:[1,0,1]
	v_pk_fma_f32 v[22:23], v[14:15], v[24:25], v[0:1] op_sel_hi:[1,1,0] neg_lo:[0,0,1] neg_hi:[0,0,1]
	v_mul_f32_e32 v0, v14, v25
	v_pk_fma_f32 v[24:25], v[14:15], v[24:25], v[0:1] op_sel:[1,0,0] op_sel_hi:[0,1,0]
	v_mul_f32_e32 v0, v13, v21
	v_pk_mul_f32 v[14:15], v[10:11], v[18:19]
	v_pk_fma_f32 v[10:11], v[10:11], v[18:19], v[94:95] op_sel_hi:[1,0,1]
	v_pk_fma_f32 v[18:19], v[12:13], v[20:21], v[0:1] op_sel_hi:[1,1,0] neg_lo:[0,0,1] neg_hi:[0,0,1]
	v_mul_f32_e32 v0, v12, v21
	v_pk_fma_f32 v[20:21], v[12:13], v[20:21], v[0:1] op_sel:[1,0,0] op_sel_hi:[0,1,0]
	v_sub_f32_e32 v10, v14, v94
	v_sub_f32_e32 v8, v90, v92
	v_mov_b32_e32 v12, v18
	v_mov_b32_e32 v13, v20
	v_mov_b32_e32 v14, v22
	v_mov_b32_e32 v15, v24
.LBB0_1107:
	s_or_b64 exec, exec, s[16:17]
	v_cvt_pk_bf16_f32 v8, v8, v9
	v_cvt_pk_bf16_f32 v9, v14, v15
	v_cvt_pk_bf16_f32 v10, v10, v11
	v_cvt_pk_bf16_f32 v11, v12, v13
	global_store_dwordx4 v[6:7], v[8:11], off offset:256
	v_add_u32_e32 v6, 0x80, v16
	v_lshlrev_b32_e32 v0, 5, v6
	v_and_b32_e32 v0, 0xf9e0, v0
	v_pk_mul_f32 v[14:15], v[88:89], s[58:59] op_sel_hi:[1,0]
	v_pk_mul_f32 v[8:9], v[86:87], s[58:59] op_sel_hi:[1,0]
	v_pk_mul_f32 v[12:13], v[84:85], s[58:59] op_sel_hi:[1,0]
	v_pk_mul_f32 v[10:11], v[82:83], s[58:59] op_sel_hi:[1,0]
	s_and_b64 vcc, exec, s[12:13]
	v_lshlrev_b32_e32 v0, 3, v0
	v_mov_b32_e32 v238, v2
	v_mov_b32_e32 v239, 0
	v_add_u32_e32 v236, 128, v16
	v_lshlrev_b32_e32 v236, 5, v236
	v_and_b32_e32 v236, 0xffe0, v236
	v_lshlrev_b32_e32 v236, 3, v236
	v_mov_b32_e32 v237, 0
	v_lshl_add_u64 v[236:237], s[52:53], 0, v[236:237]
	v_lshl_add_u64 v[236:237], v[236:237], 0, v[238:239]
	global_load_dwordx4 v[186:189], v[236:237], off offset:16
	global_load_dwordx4 v[190:193], v[236:237], off
	v_add_u32_e32 v236, 144, v16
	v_lshlrev_b32_e32 v236, 5, v236
	v_and_b32_e32 v236, 0xffe0, v236
	v_lshlrev_b32_e32 v236, 3, v236
	v_mov_b32_e32 v237, 0
	v_lshl_add_u64 v[236:237], s[52:53], 0, v[236:237]
	v_lshl_add_u64 v[236:237], v[236:237], 0, v[238:239]
	global_load_dwordx4 v[194:197], v[236:237], off offset:16
	global_load_dwordx4 v[198:201], v[236:237], off
	v_add_u32_e32 v236, 160, v16
	v_lshlrev_b32_e32 v236, 5, v236
	v_and_b32_e32 v236, 0xffe0, v236
	v_lshlrev_b32_e32 v236, 3, v236
	v_mov_b32_e32 v237, 0
	v_lshl_add_u64 v[236:237], s[52:53], 0, v[236:237]
	v_lshl_add_u64 v[236:237], v[236:237], 0, v[238:239]
	global_load_dwordx4 v[202:205], v[236:237], off offset:16
	global_load_dwordx4 v[206:209], v[236:237], off
	s_waitcnt vmcnt(0)
	s_cbranch_vccnz .LBB0_1109
	v_mov_b32_e32 v3, v1
	v_mov_b32_e32 v18, v186
	v_mov_b32_e32 v19, v187
	v_mov_b32_e32 v20, v188
	v_mov_b32_e32 v21, v189
	v_mov_b32_e32 v22, v190
	v_mov_b32_e32 v23, v191
	v_mov_b32_e32 v24, v192
	v_mov_b32_e32 v25, v193
	v_pk_mul_f32 v[86:87], v[10:11], v[18:19] op_sel:[1,1] op_sel_hi:[0,1]
	v_pk_mul_f32 v[84:85], v[8:9], v[22:23] op_sel:[1,1] op_sel_hi:[0,1]
	v_pk_mul_f32 v[82:83], v[8:9], v[22:23]
	v_pk_fma_f32 v[8:9], v[8:9], v[22:23], v[84:85] op_sel_hi:[1,0,1]
	s_nop 0
	v_mul_f32_e32 v8, v15, v25
	v_pk_fma_f32 v[22:23], v[14:15], v[24:25], v[8:9] op_sel_hi:[1,1,0] neg_lo:[0,0,1] neg_hi:[0,0,1]
	v_mul_f32_e32 v8, v14, v25
	v_pk_fma_f32 v[24:25], v[14:15], v[24:25], v[8:9] op_sel:[1,0,0] op_sel_hi:[0,1,0]
	v_mul_f32_e32 v8, v13, v21
	v_pk_mul_f32 v[14:15], v[10:11], v[18:19]
	v_pk_fma_f32 v[10:11], v[10:11], v[18:19], v[86:87] op_sel_hi:[1,0,1]
	v_pk_fma_f32 v[18:19], v[12:13], v[20:21], v[8:9] op_sel_hi:[1,1,0] neg_lo:[0,0,1] neg_hi:[0,0,1]
	v_mul_f32_e32 v8, v12, v21
	v_pk_fma_f32 v[20:21], v[12:13], v[20:21], v[8:9] op_sel:[1,0,0] op_sel_hi:[0,1,0]
	v_sub_f32_e32 v10, v14, v86
	v_sub_f32_e32 v8, v82, v84
	v_mov_b32_e32 v12, v18
	v_mov_b32_e32 v13, v20
	v_mov_b32_e32 v14, v22
	v_mov_b32_e32 v15, v24
;   DI void operator()(const f32x4 (&acc)[2][2][4][2], const pg8::Unit& u, int wr, int wc, int fr, int fq) const {
;     const int row0 = u.pm * 256 + wr * 64 + fr, colb = u.pn * 256 + wc * 32 + 8 * fq;
; #pragma unroll
;     for (int ai = 0; ai < 2; ++ai)
; #pragma unroll
;       for (int m = 0; m < 4; ++m) {
;         const int row = row0 + ai * 128 + m * 16;
; #pragma unroll
;         for (int bj = 0; bj < 2; ++bj) {
;           const int col = colb + bj * 128;
;           f32x4 v0 = acc[ai][bj][m][0] * sc, v1 = acc[ai][bj][m][1] * sc;
;           u16* dst = nullptr;
;           if (MODE == 0) { if (col < N) dst = d0 + (size_t)row * ld0 + (col + coff2 + ((col < csplit) ? (coff1 - coff2) : 0)); }
;           else if (MODE == 1) {
;             const int oc = col + coff2 + ((col < csplit) ? (coff1 - coff2) : 0);
;             if (col < N) {
;               if (oc < 2048) dst = d0 + (size_t)row * 2048 + oc;
;               else if (oc < 2112) { rot(v0, v1, row, oc); dst = d2 + (size_t)row * 64 + (oc - 2048); }
;               else dst = d1 + (size_t)row * 4096 + (oc - 2112);
;             }
;           } else if (MODE == 3) {
;             if (col < N) { const bool lo = col < csplit; u16* bp = lo ? d0 : d1; const int ldd = lo ? 2048 : 4096, oc = lo ? col : col + (coff2 - 2112); dst = bp + (size_t)row * ldd + oc + (lo ? coff1 : 0); }
;           } else {
;             if (((col >> 6) % 3) == 2) rot(v0, v1, row, col);
;             dst = d0 + (size_t)row * 3072 + col;
;           }
;           if (dst) { u32x4 w = {pk2(v0[0], v0[1]), pk2(v0[2], v0[3]), pk2(v1[0], v1[1]), pk2(v1[2], v1[3])}; *(u32x4*)dst = w; }
.LBB0_1109:
	v_mov_b64_e32 v[18:19], s[74:75]
	s_movk_i32 s16, 0x1800
	v_mad_i64_i32 v[6:7], s[16:17], v6, s16, v[18:19]
	v_lshl_add_u64 v[6:7], v[4:5], 1, v[6:7]
	v_cvt_pk_bf16_f32 v8, v8, v9
	v_cvt_pk_bf16_f32 v9, v14, v15
	v_cvt_pk_bf16_f32 v10, v10, v11
	v_cvt_pk_bf16_f32 v11, v12, v13
	global_store_dwordx4 v[6:7], v[8:11], off
	v_pk_mul_f32 v[14:15], v[80:81], s[58:59] op_sel_hi:[1,0]
	v_pk_mul_f32 v[12:13], v[76:77], s[58:59] op_sel_hi:[1,0]
	v_pk_mul_f32 v[8:9], v[78:79], s[58:59] op_sel_hi:[1,0]
	v_pk_mul_f32 v[10:11], v[74:75], s[58:59] op_sel_hi:[1,0]
	s_and_saveexec_b64 s[16:17], s[10:11]
	s_cbranch_execz .LBB0_1111
	v_mov_b32_e32 v3, v1
	v_mov_b32_e32 v18, v186
	v_mov_b32_e32 v19, v187
	v_mov_b32_e32 v20, v188
	v_mov_b32_e32 v21, v189
	v_mov_b32_e32 v22, v190
	v_mov_b32_e32 v23, v191
	v_mov_b32_e32 v24, v192
	v_mov_b32_e32 v25, v193
	v_pk_mul_f32 v[78:79], v[10:11], v[18:19] op_sel:[1,1] op_sel_hi:[0,1]
	v_pk_mul_f32 v[76:77], v[8:9], v[22:23] op_sel:[1,1] op_sel_hi:[0,1]
	v_mul_f32_e32 v0, v15, v25
	v_pk_mul_f32 v[74:75], v[8:9], v[22:23]
	v_pk_fma_f32 v[8:9], v[8:9], v[22:23], v[76:77] op_sel_hi:[1,0,1]
	v_pk_fma_f32 v[22:23], v[14:15], v[24:25], v[0:1] op_sel_hi:[1,1,0] neg_lo:[0,0,1] neg_hi:[0,0,1]
	v_mul_f32_e32 v0, v14, v25
	v_pk_fma_f32 v[24:25], v[14:15], v[24:25], v[0:1] op_sel:[1,0,0] op_sel_hi:[0,1,0]
	v_mul_f32_e32 v0, v13, v21
	v_pk_mul_f32 v[14:15], v[10:11], v[18:19]
	v_pk_fma_f32 v[10:11], v[10:11], v[18:19], v[78:79] op_sel_hi:[1,0,1]
	v_pk_fma_f32 v[18:19], v[12:13], v[20:21], v[0:1] op_sel_hi:[1,1,0] neg_lo:[0,0,1] neg_hi:[0,0,1]
	v_mul_f32_e32 v0, v12, v21
	v_pk_fma_f32 v[20:21], v[12:13], v[20:21], v[0:1] op_sel:[1,0,0] op_sel_hi:[0,1,0]
	v_sub_f32_e32 v10, v14, v78
	v_sub_f32_e32 v8, v74, v76
	v_mov_b32_e32 v12, v18
	v_mov_b32_e32 v13, v20
	v_mov_b32_e32 v14, v22
	v_mov_b32_e32 v15, v24
.LBB0_1111:
	s_or_b64 exec, exec, s[16:17]
	v_cvt_pk_bf16_f32 v8, v8, v9
	v_cvt_pk_bf16_f32 v9, v14, v15
	v_cvt_pk_bf16_f32 v10, v10, v11
	v_cvt_pk_bf16_f32 v11, v12, v13
	global_store_dwordx4 v[6:7], v[8:11], off offset:256
	v_add_u32_e32 v6, 0x90, v16
	v_lshlrev_b32_e32 v0, 5, v6
	v_and_b32_e32 v0, 0xfbe0, v0
	v_pk_mul_f32 v[14:15], v[72:73], s[58:59] op_sel_hi:[1,0]
	v_pk_mul_f32 v[8:9], v[70:71], s[58:59] op_sel_hi:[1,0]
	v_pk_mul_f32 v[12:13], v[68:69], s[58:59] op_sel_hi:[1,0]
	v_pk_mul_f32 v[10:11], v[66:67], s[58:59] op_sel_hi:[1,0]
	s_and_b64 vcc, exec, s[12:13]
	v_lshlrev_b32_e32 v0, 3, v0
	s_cbranch_vccnz .LBB0_1113
	v_mov_b32_e32 v3, v1
	v_mov_b32_e32 v18, v194
	v_mov_b32_e32 v19, v195
	v_mov_b32_e32 v20, v196
	v_mov_b32_e32 v21, v197
	v_mov_b32_e32 v22, v198
	v_mov_b32_e32 v23, v199
	v_mov_b32_e32 v24, v200
	v_mov_b32_e32 v25, v201
	v_pk_mul_f32 v[70:71], v[10:11], v[18:19] op_sel:[1,1] op_sel_hi:[0,1]
	v_pk_mul_f32 v[68:69], v[8:9], v[22:23] op_sel:[1,1] op_sel_hi:[0,1]
	v_pk_mul_f32 v[66:67], v[8:9], v[22:23]
	v_pk_fma_f32 v[8:9], v[8:9], v[22:23], v[68:69] op_sel_hi:[1,0,1]
	s_nop 0
	v_mul_f32_e32 v8, v15, v25
	v_pk_fma_f32 v[22:23], v[14:15], v[24:25], v[8:9] op_sel_hi:[1,1,0] neg_lo:[0,0,1] neg_hi:[0,0,1]
	v_mul_f32_e32 v8, v14, v25
	v_pk_fma_f32 v[24:25], v[14:15], v[24:25], v[8:9] op_sel:[1,0,0] op_sel_hi:[0,1,0]
	v_mul_f32_e32 v8, v13, v21
	v_pk_mul_f32 v[14:15], v[10:11], v[18:19]
	v_pk_fma_f32 v[10:11], v[10:11], v[18:19], v[70:71] op_sel_hi:[1,0,1]
	v_pk_fma_f32 v[18:19], v[12:13], v[20:21], v[8:9] op_sel_hi:[1,1,0] neg_lo:[0,0,1] neg_hi:[0,0,1]
	v_mul_f32_e32 v8, v12, v21
	v_pk_fma_f32 v[20:21], v[12:13], v[20:21], v[8:9] op_sel:[1,0,0] op_sel_hi:[0,1,0]
	v_sub_f32_e32 v10, v14, v70
	v_sub_f32_e32 v8, v66, v68
	v_mov_b32_e32 v12, v18
	v_mov_b32_e32 v13, v20
	v_mov_b32_e32 v14, v22
	v_mov_b32_e32 v15, v24
;   DI void operator()(const f32x4 (&acc)[2][2][4][2], const pg8::Unit& u, int wr, int wc, int fr, int fq) const {
;     const int row0 = u.pm * 256 + wr * 64 + fr, colb = u.pn * 256 + wc * 32 + 8 * fq;
; #pragma unroll
;     for (int ai = 0; ai < 2; ++ai)
; #pragma unroll
;       for (int m = 0; m < 4; ++m) {
;         const int row = row0 + ai * 128 + m * 16;
; #pragma unroll
;         for (int bj = 0; bj < 2; ++bj) {
;           const int col = colb + bj * 128;
;           f32x4 v0 = acc[ai][bj][m][0] * sc, v1 = acc[ai][bj][m][1] * sc;
;           u16* dst = nullptr;
;           if (MODE == 0) { if (col < N) dst = d0 + (size_t)row * ld0 + (col + coff2 + ((col < csplit) ? (coff1 - coff2) : 0)); }
;           else if (MODE == 1) {
;             const int oc = col + coff2 + ((col < csplit) ? (coff1 - coff2) : 0);
;             if (col < N) {
;               if (oc < 2048) dst = d0 + (size_t)row * 2048 + oc;
;               else if (oc < 2112) { rot(v0, v1, row, oc); dst = d2 + (size_t)row * 64 + (oc - 2048); }
;               else dst = d1 + (size_t)row * 4096 + (oc - 2112);
;             }
;           } else if (MODE == 3) {
;             if (col < N) { const bool lo = col < csplit; u16* bp = lo ? d0 : d1; const int ldd = lo ? 2048 : 4096, oc = lo ? col : col + (coff2 - 2112); dst = bp + (size_t)row * ldd + oc + (lo ? coff1 : 0); }
;           } else {
;             if (((col >> 6) % 3) == 2) rot(v0, v1, row, col);
;             dst = d0 + (size_t)row * 3072 + col;
;           }
;           if (dst) { u32x4 w = {pk2(v0[0], v0[1]), pk2(v0[2], v0[3]), pk2(v1[0], v1[1]), pk2(v1[2], v1[3])}; *(u32x4*)dst = w; }
.LBB0_1113:
	v_mov_b64_e32 v[18:19], s[74:75]
	s_movk_i32 s16, 0x1800
	v_mad_i64_i32 v[6:7], s[16:17], v6, s16, v[18:19]
	v_lshl_add_u64 v[6:7], v[4:5], 1, v[6:7]
	v_cvt_pk_bf16_f32 v8, v8, v9
	v_cvt_pk_bf16_f32 v9, v14, v15
	v_cvt_pk_bf16_f32 v10, v10, v11
	v_cvt_pk_bf16_f32 v11, v12, v13
	global_store_dwordx4 v[6:7], v[8:11], off
	v_pk_mul_f32 v[14:15], v[64:65], s[58:59] op_sel_hi:[1,0]
	v_pk_mul_f32 v[12:13], v[60:61], s[58:59] op_sel_hi:[1,0]
	v_pk_mul_f32 v[8:9], v[62:63], s[58:59] op_sel_hi:[1,0]
	v_pk_mul_f32 v[10:11], v[58:59], s[58:59] op_sel_hi:[1,0]
	s_and_saveexec_b64 s[16:17], s[10:11]
	s_cbranch_execz .LBB0_1115
	v_mov_b32_e32 v3, v1
	v_mov_b32_e32 v18, v194
	v_mov_b32_e32 v19, v195
	v_mov_b32_e32 v20, v196
	v_mov_b32_e32 v21, v197
	v_mov_b32_e32 v22, v198
	v_mov_b32_e32 v23, v199
	v_mov_b32_e32 v24, v200
	v_mov_b32_e32 v25, v201
	v_pk_mul_f32 v[62:63], v[10:11], v[18:19] op_sel:[1,1] op_sel_hi:[0,1]
	v_pk_mul_f32 v[60:61], v[8:9], v[22:23] op_sel:[1,1] op_sel_hi:[0,1]
	v_mul_f32_e32 v0, v15, v25
	v_pk_mul_f32 v[58:59], v[8:9], v[22:23]
	v_pk_fma_f32 v[8:9], v[8:9], v[22:23], v[60:61] op_sel_hi:[1,0,1]
	v_pk_fma_f32 v[22:23], v[14:15], v[24:25], v[0:1] op_sel_hi:[1,1,0] neg_lo:[0,0,1] neg_hi:[0,0,1]
	v_mul_f32_e32 v0, v14, v25
	v_pk_fma_f32 v[24:25], v[14:15], v[24:25], v[0:1] op_sel:[1,0,0] op_sel_hi:[0,1,0]
	v_mul_f32_e32 v0, v13, v21
	v_pk_mul_f32 v[14:15], v[10:11], v[18:19]
	v_pk_fma_f32 v[10:11], v[10:11], v[18:19], v[62:63] op_sel_hi:[1,0,1]
	v_pk_fma_f32 v[18:19], v[12:13], v[20:21], v[0:1] op_sel_hi:[1,1,0] neg_lo:[0,0,1] neg_hi:[0,0,1]
	v_mul_f32_e32 v0, v12, v21
	v_pk_fma_f32 v[20:21], v[12:13], v[20:21], v[0:1] op_sel:[1,0,0] op_sel_hi:[0,1,0]
	v_sub_f32_e32 v10, v14, v62
	v_sub_f32_e32 v8, v58, v60
	v_mov_b32_e32 v12, v18
	v_mov_b32_e32 v13, v20
	v_mov_b32_e32 v14, v22
	v_mov_b32_e32 v15, v24
.LBB0_1115:
	s_or_b64 exec, exec, s[16:17]
	v_cvt_pk_bf16_f32 v8, v8, v9
	v_cvt_pk_bf16_f32 v9, v14, v15
	v_cvt_pk_bf16_f32 v10, v10, v11
	v_cvt_pk_bf16_f32 v11, v12, v13
	global_store_dwordx4 v[6:7], v[8:11], off offset:256
	v_add_u32_e32 v6, 0xa0, v16
	v_lshlrev_b32_e32 v0, 5, v6
	v_and_b32_e32 v0, 0xfde0, v0
	v_pk_mul_f32 v[14:15], v[56:57], s[58:59] op_sel_hi:[1,0]
	v_pk_mul_f32 v[8:9], v[54:55], s[58:59] op_sel_hi:[1,0]
	v_pk_mul_f32 v[12:13], v[52:53], s[58:59] op_sel_hi:[1,0]
	v_pk_mul_f32 v[10:11], v[50:51], s[58:59] op_sel_hi:[1,0]
	s_and_b64 vcc, exec, s[12:13]
	v_lshlrev_b32_e32 v0, 3, v0
	s_cbranch_vccnz .LBB0_1117
	v_mov_b32_e32 v3, v1
	v_mov_b32_e32 v18, v202
	v_mov_b32_e32 v19, v203
	v_mov_b32_e32 v20, v204
	v_mov_b32_e32 v21, v205
	v_mov_b32_e32 v22, v206
	v_mov_b32_e32 v23, v207
	v_mov_b32_e32 v24, v208
	v_mov_b32_e32 v25, v209
	v_pk_mul_f32 v[54:55], v[10:11], v[18:19] op_sel:[1,1] op_sel_hi:[0,1]
	v_pk_mul_f32 v[52:53], v[8:9], v[22:23] op_sel:[1,1] op_sel_hi:[0,1]
	v_pk_mul_f32 v[50:51], v[8:9], v[22:23]
	v_pk_fma_f32 v[8:9], v[8:9], v[22:23], v[52:53] op_sel_hi:[1,0,1]
	s_nop 0
	v_mul_f32_e32 v8, v15, v25
	v_pk_fma_f32 v[22:23], v[14:15], v[24:25], v[8:9] op_sel_hi:[1,1,0] neg_lo:[0,0,1] neg_hi:[0,0,1]
	v_mul_f32_e32 v8, v14, v25
	v_pk_fma_f32 v[24:25], v[14:15], v[24:25], v[8:9] op_sel:[1,0,0] op_sel_hi:[0,1,0]
	v_mul_f32_e32 v8, v13, v21
	v_pk_mul_f32 v[14:15], v[10:11], v[18:19]
	v_pk_fma_f32 v[10:11], v[10:11], v[18:19], v[54:55] op_sel_hi:[1,0,1]
	v_pk_fma_f32 v[18:19], v[12:13], v[20:21], v[8:9] op_sel_hi:[1,1,0] neg_lo:[0,0,1] neg_hi:[0,0,1]
	v_mul_f32_e32 v8, v12, v21
	v_pk_fma_f32 v[20:21], v[12:13], v[20:21], v[8:9] op_sel:[1,0,0] op_sel_hi:[0,1,0]
	v_sub_f32_e32 v10, v14, v54
	v_sub_f32_e32 v8, v50, v52
	v_mov_b32_e32 v12, v18
	v_mov_b32_e32 v13, v20
	v_mov_b32_e32 v14, v22
	v_mov_b32_e32 v15, v24
.LBB0_1117:
	v_mov_b64_e32 v[18:19], s[74:75]
	s_movk_i32 s16, 0x1800
	v_mad_i64_i32 v[6:7], s[16:17], v6, s16, v[18:19]
	v_lshl_add_u64 v[6:7], v[4:5], 1, v[6:7]
	v_cvt_pk_bf16_f32 v8, v8, v9
	v_cvt_pk_bf16_f32 v9, v14, v15
	v_cvt_pk_bf16_f32 v10, v10, v11
	v_cvt_pk_bf16_f32 v11, v12, v13
	global_store_dwordx4 v[6:7], v[8:11], off
	v_pk_mul_f32 v[14:15], v[48:49], s[58:59] op_sel_hi:[1,0]
	v_pk_mul_f32 v[12:13], v[44:45], s[58:59] op_sel_hi:[1,0]
	v_pk_mul_f32 v[8:9], v[46:47], s[58:59] op_sel_hi:[1,0]
	v_pk_mul_f32 v[10:11], v[42:43], s[58:59] op_sel_hi:[1,0]
	s_and_saveexec_b64 s[16:17], s[10:11]
	s_cbranch_execz .LBB0_1119
	v_mov_b32_e32 v3, v1
	v_mov_b32_e32 v18, v202
	v_mov_b32_e32 v19, v203
	v_mov_b32_e32 v20, v204
	v_mov_b32_e32 v21, v205
	v_mov_b32_e32 v22, v206
	v_mov_b32_e32 v23, v207
	v_mov_b32_e32 v24, v208
	v_mov_b32_e32 v25, v209
	v_pk_mul_f32 v[46:47], v[10:11], v[18:19] op_sel:[1,1] op_sel_hi:[0,1]
	v_pk_mul_f32 v[44:45], v[8:9], v[22:23] op_sel:[1,1] op_sel_hi:[0,1]
	v_mul_f32_e32 v0, v15, v25
	v_pk_mul_f32 v[42:43], v[8:9], v[22:23]
	v_pk_fma_f32 v[8:9], v[8:9], v[22:23], v[44:45] op_sel_hi:[1,0,1]
	v_pk_fma_f32 v[22:23], v[14:15], v[24:25], v[0:1] op_sel_hi:[1,1,0] neg_lo:[0,0,1] neg_hi:[0,0,1]
	v_mul_f32_e32 v0, v14, v25
	v_pk_fma_f32 v[24:25], v[14:15], v[24:25], v[0:1] op_sel:[1,0,0] op_sel_hi:[0,1,0]
	v_mul_f32_e32 v0, v13, v21
	v_pk_mul_f32 v[14:15], v[10:11], v[18:19]
	v_pk_fma_f32 v[10:11], v[10:11], v[18:19], v[46:47] op_sel_hi:[1,0,1]
	v_pk_fma_f32 v[18:19], v[12:13], v[20:21], v[0:1] op_sel_hi:[1,1,0] neg_lo:[0,0,1] neg_hi:[0,0,1]
	v_mul_f32_e32 v0, v12, v21
	v_pk_fma_f32 v[20:21], v[12:13], v[20:21], v[0:1] op_sel:[1,0,0] op_sel_hi:[0,1,0]
	v_sub_f32_e32 v10, v14, v46
	v_sub_f32_e32 v8, v42, v44
	v_mov_b32_e32 v12, v18
	v_mov_b32_e32 v13, v20
	v_mov_b32_e32 v14, v22
	v_mov_b32_e32 v15, v24
